# Griffin tile loop: latch waits vmcnt(4) (output stores no longer waited every tile) + cg loads waited at use
# speedup vs baseline: 1.0196x; 1.0068x over previous
.LBB0_482:
	s_or_b64 exec, exec, s[28:29]
	s_waitcnt vmcnt(4)
	s_branch .Lgr_latch_common

.Lgr_latch_common:
	s_cmp_eq_u32 s45, 64
	s_mov_b32 s16, s45
	v_mov_b32_e32 v160, v14
	v_mov_b32_e32 v161, v15
	v_mov_b32_e32 v162, v30
	v_mov_b32_e32 v163, v31
	v_mov_b32_e32 v164, v46
	v_mov_b32_e32 v165, v47
	v_mov_b32_e32 v166, v62
	v_mov_b32_e32 v167, v63
	v_mov_b32_e32 v168, v16
	v_mov_b32_e32 v169, v17
	v_mov_b32_e32 v170, v32
	v_mov_b32_e32 v171, v33
	v_mov_b32_e32 v172, v48
	v_mov_b32_e32 v173, v49
	v_mov_b32_e32 v176, v64
	v_mov_b32_e32 v177, v65
	v_mov_b32_e32 v174, v6
	v_mov_b32_e32 v175, v7
	v_mov_b32_e32 v178, v22
	v_mov_b32_e32 v179, v23
	v_mov_b32_e32 v180, v38
	v_mov_b32_e32 v181, v39
	v_mov_b32_e32 v182, v54
	v_mov_b32_e32 v183, v55
	v_mov_b32_e32 v184, v8
	v_mov_b32_e32 v185, v9
	v_mov_b32_e32 v186, v24
	v_mov_b32_e32 v187, v25
	v_mov_b32_e32 v188, v40
	v_mov_b32_e32 v189, v41
	v_mov_b32_e32 v192, v56
	v_mov_b32_e32 v193, v57
	v_mov_b32_e32 v190, v10
	v_mov_b32_e32 v191, v11
	v_mov_b32_e32 v194, v26
	v_mov_b32_e32 v195, v27
	v_mov_b32_e32 v196, v42
	v_mov_b32_e32 v197, v43
	v_mov_b32_e32 v198, v58
	v_mov_b32_e32 v199, v59
	v_mov_b32_e32 v200, v12
	v_mov_b32_e32 v201, v13
	v_mov_b32_e32 v202, v28
	v_mov_b32_e32 v203, v29
	v_mov_b32_e32 v204, v44
	v_mov_b32_e32 v205, v45
	v_mov_b32_e32 v208, v60
	v_mov_b32_e32 v209, v61
	v_mov_b32_e32 v206, v2
	v_mov_b32_e32 v207, v3
	v_mov_b32_e32 v210, v18
	v_mov_b32_e32 v211, v19
	v_mov_b32_e32 v212, v34
	v_mov_b32_e32 v213, v35
	v_mov_b32_e32 v214, v50
	v_mov_b32_e32 v215, v51
	v_mov_b32_e32 v216, v4
	v_mov_b32_e32 v217, v5
	v_mov_b32_e32 v218, v20
	v_mov_b32_e32 v219, v21
	v_mov_b32_e32 v220, v36
	v_mov_b32_e32 v221, v37
	v_mov_b32_e32 v222, v52
	v_mov_b32_e32 v223, v53
	s_cbranch_scc1 .LBB0_470
